# last layer's FFN-down epilogue no longer stores the next-layer operand xg (nothing reads it after layer 3)
# speedup vs baseline: 1.0054x; 1.0054x over previous
.Lsk_epi:
	v_readlane_b32 s32, v255, 22
	v_mbcnt_lo_u32_b32 v64, -1, 0
	v_mbcnt_hi_u32_b32 v64, -1, v64
	s_add_i32 s95, s95, s39
	v_ashrrev_i32_e32 v65, 1, v64
	v_and_or_b32 v242, v64, 15, s95
	s_or_b32 s78, s80, s53
	v_and_b32_e32 v65, -8, v65
	v_lshlrev_b32_e32 v220, 13, v242
	v_add_lshl_u32 v241, s78, v65, 1
	v_add_u32_e32 v221, v241, v220
	global_load_dwordx4 v[244:247], v221, s[20:21]
	s_add_i32 s67, s67, s68
	v_cmp_gt_u32_e32 vcc, 16, v64
	v_add_lshl_u32 v64, v65, s53, 2
	v_add_u32_e32 v243, s67, v64
	v_add_u32_e32 v64, 0x100, v221
	global_load_dwordx4 v[248:251], v64, s[20:21]
	v_add_u32_e32 v65, 0x20000, v221
	v_add_u32_e32 v66, 0x20100, v221
	v_add_u32_e32 v67, 0x40000, v221
	v_add_u32_e32 v72, 0x40100, v221
	v_add_u32_e32 v64, 0x60000, v221
	v_add_u32_e32 v73, 0x60100, v221
	v_add_u32_e32 v74, 0x100000, v221
	v_add_u32_e32 v75, 0x100100, v221
	v_add_u32_e32 v88, 0x120000, v221
	v_add_u32_e32 v89, 0x120100, v221
	v_add_u32_e32 v90, 0x140000, v221
	v_add_u32_e32 v91, 0x140100, v221
	v_add_u32_e32 v152, 0x160000, v221
	v_add_u32_e32 v153, 0x160100, v221
	global_load_dwordx4 v[212:215], v65, s[20:21]
	global_load_dwordx4 v[208:211], v66, s[20:21]
	global_load_dwordx4 v[204:207], v67, s[20:21]
	global_load_dwordx4 v[200:203], v72, s[20:21]
	global_load_dwordx4 v[192:195], v64, s[20:21]
	global_load_dwordx4 v[164:167], v73, s[20:21]
	global_load_dwordx4 v[140:143], v74, s[20:21]
	global_load_dwordx4 v[128:131], v75, s[20:21]
	global_load_dwordx4 v[116:119], v88, s[20:21]
	global_load_dwordx4 v[108:111], v89, s[20:21]
	global_load_dwordx4 v[96:99], v90, s[20:21]
	s_nop 0
	global_load_dwordx4 v[88:91], v91, s[20:21]
	s_nop 0
	global_load_dwordx4 v[72:75], v152, s[20:21]
	global_load_dwordx4 v[64:67], v153, s[20:21]
	s_waitcnt vmcnt(0)
	ds_read_b128 v[196:199], v243
	ds_read_b128 v[188:191], v243 offset:16
	ds_read_b128 v[184:187], v243 offset:4096
	ds_read_b128 v[180:183], v243 offset:4112
	ds_read_b128 v[168:171], v243 offset:512
	ds_read_b128 v[160:163], v243 offset:528
	ds_read_b128 v[156:159], v243 offset:4608
	ds_read_b128 v[152:155], v243 offset:4624
	v_lshlrev_b32_e32 v235, 12, v242
	s_waitcnt vmcnt(0)
	v_lshlrev_b32_e32 v218, 16, v244
	v_and_b32_e32 v219, 0xffff0000, v244
	v_lshlrev_b32_e32 v252, 16, v246
	v_and_b32_e32 v253, 0xffff0000, v246
	v_lshlrev_b32_e32 v246, 16, v247
	v_and_b32_e32 v247, 0xffff0000, v247
	v_lshlrev_b32_e32 v244, 16, v245
	v_and_b32_e32 v245, 0xffff0000, v245
	s_waitcnt lgkmcnt(7)
	v_pk_fma_f32 v[176:177], v[176:177], v[196:197], v[218:219]
	s_waitcnt lgkmcnt(6)
	v_pk_fma_f32 v[218:219], v[174:175], v[190:191], v[246:247]
	v_pk_fma_f32 v[174:175], v[172:173], v[188:189], v[252:253]
	v_pk_fma_f32 v[178:179], v[178:179], v[198:199], v[244:245]
	v_cvt_pk_bf16_f32 v172, v176, v177
	s_nop 0
	v_cvt_pk_bf16_f32 v173, v178, v179
	v_cvt_pk_bf16_f32 v174, v174, v175
	v_cvt_pk_bf16_f32 v175, v218, v219
	global_store_dwordx4 v221, v[172:175], s[20:21]
	v_lshlrev_b32_e32 v176, 16, v172
	v_and_b32_e32 v177, 0xffff0000, v172
	v_lshlrev_b32_e32 v172, 16, v173
	v_and_b32_e32 v173, 0xffff0000, v173
	v_lshlrev_b32_e32 v178, 16, v174
	v_and_b32_e32 v179, 0xffff0000, v174
	v_lshlrev_b32_e32 v174, 16, v175
	v_and_b32_e32 v175, 0xffff0000, v175
	v_mul_f32_e32 v221, v177, v177
	v_mul_f32_e32 v236, v173, v173
	v_mul_f32_e32 v252, v179, v179
	v_mul_f32_e32 v253, v175, v175
	v_fmac_f32_e32 v221, v176, v176
	v_fmac_f32_e32 v236, v172, v172
	v_fmac_f32_e32 v252, v178, v178
	v_fmac_f32_e32 v253, v174, v174
	s_waitcnt lgkmcnt(5)
	v_pk_mul_f32 v[218:219], v[186:187], v[172:173]
	v_add_f32_e32 v172, v221, v236
	v_add_f32_e32 v173, v252, v253
	v_pk_mul_f32 v[244:245], v[184:185], v[176:177]
	s_waitcnt lgkmcnt(4)
	v_pk_mul_f32 v[246:247], v[182:183], v[174:175]
	v_add_f32_e32 v221, v172, v173
	v_pk_mul_f32 v[174:175], v[180:181], v[178:179]
	v_cvt_pk_bf16_f32 v172, v244, v245
	v_cvt_pk_bf16_f32 v173, v218, v219
	v_add_u32_e32 v176, v241, v235
	v_cvt_pk_bf16_f32 v174, v174, v175
	v_cvt_pk_bf16_f32 v175, v246, v247
	s_cmp_eq_u32 s32, 3
	s_cbranch_scc1 .Lxg3_0
	global_store_dwordx4 v176, v[172:175], s[22:23]
.Lxg3_0:
	v_lshlrev_b32_e32 v176, 16, v250
	v_and_b32_e32 v177, 0xffff0000, v250
	v_lshlrev_b32_e32 v172, 16, v248
	v_and_b32_e32 v173, 0xffff0000, v248
	v_lshlrev_b32_e32 v174, 16, v249
	v_and_b32_e32 v175, 0xffff0000, v249
	v_lshlrev_b32_e32 v178, 16, v251
	v_and_b32_e32 v179, 0xffff0000, v251
	s_waitcnt lgkmcnt(3)
	v_pk_fma_f32 v[148:149], v[148:149], v[168:169], v[172:173]
	s_waitcnt lgkmcnt(2)
	v_pk_fma_f32 v[144:145], v[144:145], v[160:161], v[176:177]
	v_pk_fma_f32 v[150:151], v[150:151], v[170:171], v[174:175]
	v_pk_fma_f32 v[172:173], v[146:147], v[162:163], v[178:179]
	v_cvt_pk_bf16_f32 v146, v148, v149
	v_cvt_pk_bf16_f32 v147, v150, v151
	v_cvt_pk_bf16_f32 v148, v144, v145
	v_add_u32_e32 v144, 0x100, v241
	v_add_u32_e32 v145, v144, v220
	v_cvt_pk_bf16_f32 v149, v172, v173
	global_store_dwordx4 v145, v[146:149], s[20:21]
	v_lshlrev_b32_e32 v150, 16, v146
	v_and_b32_e32 v151, 0xffff0000, v146
	v_lshlrev_b32_e32 v146, 16, v147
	v_and_b32_e32 v147, 0xffff0000, v147
	v_mul_f32_e32 v174, v151, v151
	v_mul_f32_e32 v175, v147, v147
	v_lshlrev_b32_e32 v172, 16, v148
	v_and_b32_e32 v173, 0xffff0000, v148
	v_lshlrev_b32_e32 v148, 16, v149
	v_and_b32_e32 v149, 0xffff0000, v149
	v_fmac_f32_e32 v174, v150, v150
	v_fmac_f32_e32 v175, v146, v146
	v_add_f32_e32 v174, v174, v175
	v_mul_f32_e32 v175, v173, v173
	v_mul_f32_e32 v176, v149, v149
	v_fmac_f32_e32 v175, v172, v172
	v_fmac_f32_e32 v176, v148, v148
	v_add_f32_e32 v175, v175, v176
	v_add_f32_e32 v174, v174, v175
	v_add_f32_e32 v176, v221, v174
	s_waitcnt lgkmcnt(1)
	v_pk_mul_f32 v[174:175], v[158:159], v[146:147]
	v_pk_mul_f32 v[146:147], v[156:157], v[150:151]
	s_waitcnt lgkmcnt(0)
	v_pk_mul_f32 v[150:151], v[154:155], v[148:149]
	v_pk_mul_f32 v[148:149], v[152:153], v[172:173]
	ds_swizzle_b32 v172, v176 offset:swizzle(SWAP,16)
	v_sub_u32_e32 v145, v145, v235
	v_cvt_pk_bf16_f32 v146, v146, v147
	v_cvt_pk_bf16_f32 v147, v174, v175
	v_cvt_pk_bf16_f32 v148, v148, v149
	v_cvt_pk_bf16_f32 v149, v150, v151
	s_cmp_eq_u32 s32, 3
	s_cbranch_scc1 .Lxg3_1
	global_store_dwordx4 v145, v[146:149], s[22:23]
.Lxg3_1:
	s_waitcnt lgkmcnt(0)
	v_add_f32_e32 v145, v176, v172
	v_mov_b32_e32 v146, v145
	s_nop 1
	v_permlane32_swap_b32_e32 v145, v146
	s_and_saveexec_b64 s[78:79], vcc
	s_cbranch_execz .LBB0_1295
	v_add_f32_e32 v145, v145, v146
	s_mov_b32 s67, 0x47800000
	v_fma_f32 v145, v145, s67, 0.5
	v_trunc_f32_e32 v145, v145
	v_mul_f32_e32 v146, 0x2f800000, v145
	v_floor_f32_e32 v147, v146
	v_fmac_f32_e32 v145, 0xcf800000, v147
	v_cvt_u32_f32_e32 v146, v145
	v_cvt_u32_f32_e32 v147, v147
	v_lshlrev_b32_e32 v145, 3, v242
	global_atomic_add_x2 v145, v[146:147], s[6:7]
.LBB0_1295:
	s_or_b64 exec, exec, s[78:79]
	v_or_b32_e32 v145, 16, v242
	v_lshlrev_b32_e32 v174, 13, v145
	v_lshlrev_b32_e32 v146, 16, v212
	v_and_b32_e32 v147, 0xffff0000, v212
	v_lshlrev_b32_e32 v148, 16, v213
	v_and_b32_e32 v149, 0xffff0000, v213
	v_lshlrev_b32_e32 v150, 16, v214
	v_and_b32_e32 v151, 0xffff0000, v214
	v_lshlrev_b32_e32 v172, 16, v215
	v_and_b32_e32 v173, 0xffff0000, v215
	v_pk_fma_f32 v[138:139], v[138:139], v[198:199], v[148:149]
	v_pk_fma_f32 v[136:137], v[136:137], v[196:197], v[146:147]
	v_pk_fma_f32 v[146:147], v[134:135], v[190:191], v[172:173]
	v_pk_fma_f32 v[134:135], v[132:133], v[188:189], v[150:151]
	v_cvt_pk_bf16_f32 v132, v136, v137
	v_cvt_pk_bf16_f32 v133, v138, v139
	v_add_u32_e32 v148, v241, v174
	v_cvt_pk_bf16_f32 v134, v134, v135
	v_cvt_pk_bf16_f32 v135, v146, v147
	global_store_dwordx4 v148, v[132:135], s[20:21]
	v_lshlrev_b32_e32 v136, 16, v132
	v_and_b32_e32 v137, 0xffff0000, v132
	v_lshlrev_b32_e32 v132, 16, v133
	v_and_b32_e32 v133, 0xffff0000, v133
	v_mul_f32_e32 v146, v137, v137
	v_mul_f32_e32 v147, v133, v133
	v_lshlrev_b32_e32 v138, 16, v134
	v_and_b32_e32 v139, 0xffff0000, v134
	v_lshlrev_b32_e32 v134, 16, v135
	v_and_b32_e32 v135, 0xffff0000, v135
	v_fmac_f32_e32 v146, v136, v136
	v_fmac_f32_e32 v147, v132, v132
	v_add_f32_e32 v146, v146, v147
	v_mul_f32_e32 v147, v139, v139
	v_mul_f32_e32 v149, v135, v135
	v_fmac_f32_e32 v147, v138, v138
	v_fmac_f32_e32 v149, v134, v134
	v_add_f32_e32 v147, v147, v149
	v_add_f32_e32 v149, v146, v147
	v_pk_mul_f32 v[146:147], v[186:187], v[132:133]
	v_pk_mul_f32 v[132:133], v[184:185], v[136:137]
	v_pk_mul_f32 v[136:137], v[182:183], v[134:135]
	v_pk_mul_f32 v[134:135], v[180:181], v[138:139]
	v_cvt_pk_bf16_f32 v132, v132, v133
	v_cvt_pk_bf16_f32 v133, v146, v147
	v_lshlrev_b32_e32 v146, 12, v145
	v_cvt_pk_bf16_f32 v134, v134, v135
	v_cvt_pk_bf16_f32 v135, v136, v137
	v_sub_u32_e32 v136, v148, v146
	s_cmp_eq_u32 s32, 3
	s_cbranch_scc1 .Lxg3_2
	global_store_dwordx4 v136, v[132:135], s[22:23]
.Lxg3_2:
	v_lshlrev_b32_e32 v136, 16, v210
	v_and_b32_e32 v137, 0xffff0000, v210
	v_lshlrev_b32_e32 v132, 16, v208
	v_and_b32_e32 v133, 0xffff0000, v208
	v_lshlrev_b32_e32 v134, 16, v209
	v_and_b32_e32 v135, 0xffff0000, v209
	v_lshlrev_b32_e32 v138, 16, v211
	v_and_b32_e32 v139, 0xffff0000, v211
	v_pk_fma_f32 v[126:127], v[126:127], v[170:171], v[134:135]
	v_pk_fma_f32 v[124:125], v[124:125], v[168:169], v[132:133]
	v_pk_fma_f32 v[132:133], v[122:123], v[162:163], v[138:139]
	v_pk_fma_f32 v[122:123], v[120:121], v[160:161], v[136:137]
	v_cvt_pk_bf16_f32 v120, v124, v125
	v_cvt_pk_bf16_f32 v121, v126, v127
	v_add_u32_e32 v134, v144, v174
	v_cvt_pk_bf16_f32 v122, v122, v123
	v_cvt_pk_bf16_f32 v123, v132, v133
	global_store_dwordx4 v134, v[120:123], s[20:21]
	v_lshlrev_b32_e32 v124, 16, v120
	v_and_b32_e32 v125, 0xffff0000, v120
	v_lshlrev_b32_e32 v120, 16, v121
	v_and_b32_e32 v121, 0xffff0000, v121
	v_mul_f32_e32 v132, v125, v125
	v_mul_f32_e32 v133, v121, v121
	v_lshlrev_b32_e32 v126, 16, v122
	v_and_b32_e32 v127, 0xffff0000, v122
	v_lshlrev_b32_e32 v122, 16, v123
	v_and_b32_e32 v123, 0xffff0000, v123
	v_fmac_f32_e32 v132, v124, v124
	v_fmac_f32_e32 v133, v120, v120
	v_add_f32_e32 v132, v132, v133
	v_mul_f32_e32 v133, v127, v127
	v_mul_f32_e32 v135, v123, v123
	v_fmac_f32_e32 v133, v126, v126
	v_fmac_f32_e32 v135, v122, v122
	v_add_f32_e32 v133, v133, v135
	v_add_f32_e32 v132, v132, v133
	v_add_f32_e32 v135, v149, v132
	v_pk_mul_f32 v[132:133], v[158:159], v[120:121]
	v_pk_mul_f32 v[120:121], v[156:157], v[124:125]
	v_pk_mul_f32 v[124:125], v[154:155], v[122:123]
	v_pk_mul_f32 v[122:123], v[152:153], v[126:127]
	ds_swizzle_b32 v126, v135 offset:swizzle(SWAP,16)
	v_cvt_pk_bf16_f32 v120, v120, v121
	v_cvt_pk_bf16_f32 v121, v132, v133
	v_cvt_pk_bf16_f32 v122, v122, v123
	v_cvt_pk_bf16_f32 v123, v124, v125
	v_sub_u32_e32 v124, v134, v146
	s_cmp_eq_u32 s32, 3
	s_cbranch_scc1 .Lxg3_3
	global_store_dwordx4 v124, v[120:123], s[22:23]
.Lxg3_3:
	s_waitcnt lgkmcnt(0)
	s_nop 0
	v_add_f32_e32 v120, v135, v126
	v_mov_b32_e32 v121, v120
	s_nop 1
	v_permlane32_swap_b32_e32 v120, v121
	s_and_saveexec_b64 s[78:79], vcc
	s_cbranch_execz .LBB0_1297
	v_add_f32_e32 v120, v120, v121
	s_mov_b32 s67, 0x47800000
	v_fma_f32 v120, v120, s67, 0.5
	v_trunc_f32_e32 v120, v120
	v_mul_f32_e32 v121, 0x2f800000, v120
	v_floor_f32_e32 v121, v121
	v_fmac_f32_e32 v120, 0xcf800000, v121
	v_cvt_u32_f32_e32 v120, v120
	v_cvt_u32_f32_e32 v121, v121
	v_lshlrev_b32_e32 v122, 3, v145
	global_atomic_add_x2 v122, v[120:121], s[6:7]
.LBB0_1297:
	s_or_b64 exec, exec, s[78:79]
	v_or_b32_e32 v120, 32, v242
	v_lshlrev_b32_e32 v121, 13, v120
	v_lshlrev_b32_e32 v122, 16, v204
	v_and_b32_e32 v123, 0xffff0000, v204
	v_lshlrev_b32_e32 v124, 16, v205
	v_and_b32_e32 v125, 0xffff0000, v205
	v_lshlrev_b32_e32 v126, 16, v206
	v_and_b32_e32 v127, 0xffff0000, v206
	v_lshlrev_b32_e32 v132, 16, v207
	v_and_b32_e32 v133, 0xffff0000, v207
	v_pk_fma_f32 v[114:115], v[114:115], v[198:199], v[124:125]
	v_pk_fma_f32 v[112:113], v[112:113], v[196:197], v[122:123]
	v_pk_fma_f32 v[122:123], v[106:107], v[190:191], v[132:133]
	v_pk_fma_f32 v[106:107], v[104:105], v[188:189], v[126:127]
	v_cvt_pk_bf16_f32 v104, v112, v113
	v_cvt_pk_bf16_f32 v105, v114, v115
	v_add_u32_e32 v124, v241, v121
	v_cvt_pk_bf16_f32 v106, v106, v107
	v_cvt_pk_bf16_f32 v107, v122, v123
	global_store_dwordx4 v124, v[104:107], s[20:21]
	v_lshlrev_b32_e32 v112, 16, v104
	v_and_b32_e32 v113, 0xffff0000, v104
	v_lshlrev_b32_e32 v104, 16, v105
	v_and_b32_e32 v105, 0xffff0000, v105
	v_mul_f32_e32 v122, v113, v113
	v_mul_f32_e32 v123, v105, v105
	v_lshlrev_b32_e32 v114, 16, v106
	v_and_b32_e32 v115, 0xffff0000, v106
	v_lshlrev_b32_e32 v106, 16, v107
	v_and_b32_e32 v107, 0xffff0000, v107
	v_fmac_f32_e32 v122, v112, v112
	v_fmac_f32_e32 v123, v104, v104
	v_add_f32_e32 v122, v122, v123
	v_mul_f32_e32 v123, v115, v115
	v_mul_f32_e32 v125, v107, v107
	v_fmac_f32_e32 v123, v114, v114
	v_fmac_f32_e32 v125, v106, v106
	v_add_f32_e32 v123, v123, v125
	v_add_f32_e32 v125, v122, v123
	v_pk_mul_f32 v[122:123], v[186:187], v[104:105]
	v_pk_mul_f32 v[104:105], v[184:185], v[112:113]
	v_pk_mul_f32 v[112:113], v[182:183], v[106:107]
	v_pk_mul_f32 v[106:107], v[180:181], v[114:115]
	v_cvt_pk_bf16_f32 v104, v104, v105
	v_cvt_pk_bf16_f32 v105, v122, v123
	v_lshlrev_b32_e32 v122, 12, v120
	v_cvt_pk_bf16_f32 v106, v106, v107
	v_cvt_pk_bf16_f32 v107, v112, v113
	v_sub_u32_e32 v112, v124, v122
	s_cmp_eq_u32 s32, 3
	s_cbranch_scc1 .Lxg3_4
	global_store_dwordx4 v112, v[104:107], s[22:23]
.Lxg3_4:
	v_lshlrev_b32_e32 v112, 16, v202
	v_and_b32_e32 v113, 0xffff0000, v202
	v_lshlrev_b32_e32 v104, 16, v200
	v_and_b32_e32 v105, 0xffff0000, v200
	v_lshlrev_b32_e32 v106, 16, v201
	v_and_b32_e32 v107, 0xffff0000, v201
	v_lshlrev_b32_e32 v114, 16, v203
	v_and_b32_e32 v115, 0xffff0000, v203
	v_pk_fma_f32 v[102:103], v[102:103], v[170:171], v[106:107]
	v_pk_fma_f32 v[100:101], v[100:101], v[168:169], v[104:105]
	v_pk_fma_f32 v[104:105], v[94:95], v[162:163], v[114:115]
	v_pk_fma_f32 v[94:95], v[92:93], v[160:161], v[112:113]
	v_cvt_pk_bf16_f32 v92, v100, v101
	v_cvt_pk_bf16_f32 v93, v102, v103
	v_add_u32_e32 v106, v144, v121
	v_cvt_pk_bf16_f32 v94, v94, v95
	v_cvt_pk_bf16_f32 v95, v104, v105
	global_store_dwordx4 v106, v[92:95], s[20:21]
	v_lshlrev_b32_e32 v100, 16, v92
	v_and_b32_e32 v101, 0xffff0000, v92
	v_lshlrev_b32_e32 v92, 16, v93
	v_and_b32_e32 v93, 0xffff0000, v93
	v_mul_f32_e32 v104, v101, v101
	v_mul_f32_e32 v105, v93, v93
	v_lshlrev_b32_e32 v102, 16, v94
	v_and_b32_e32 v103, 0xffff0000, v94
	v_lshlrev_b32_e32 v94, 16, v95
	v_and_b32_e32 v95, 0xffff0000, v95
	v_fmac_f32_e32 v104, v100, v100
	v_fmac_f32_e32 v105, v92, v92
	v_add_f32_e32 v104, v104, v105
	v_mul_f32_e32 v105, v103, v103
	v_mul_f32_e32 v107, v95, v95
	v_fmac_f32_e32 v105, v102, v102
	v_fmac_f32_e32 v107, v94, v94
	v_add_f32_e32 v105, v105, v107
	v_add_f32_e32 v104, v104, v105
	v_add_f32_e32 v107, v125, v104
	v_pk_mul_f32 v[104:105], v[158:159], v[92:93]
	v_pk_mul_f32 v[92:93], v[156:157], v[100:101]
	v_pk_mul_f32 v[100:101], v[154:155], v[94:95]
	v_pk_mul_f32 v[94:95], v[152:153], v[102:103]
	ds_swizzle_b32 v102, v107 offset:swizzle(SWAP,16)
	v_cvt_pk_bf16_f32 v92, v92, v93
	v_cvt_pk_bf16_f32 v93, v104, v105
	v_cvt_pk_bf16_f32 v94, v94, v95
	v_cvt_pk_bf16_f32 v95, v100, v101
	v_sub_u32_e32 v100, v106, v122
	s_cmp_eq_u32 s32, 3
	s_cbranch_scc1 .Lxg3_5
	global_store_dwordx4 v100, v[92:95], s[22:23]
.Lxg3_5:
	s_waitcnt lgkmcnt(0)
	s_nop 0
	v_add_f32_e32 v92, v107, v102
	v_mov_b32_e32 v93, v92
	s_nop 1
	v_permlane32_swap_b32_e32 v92, v93
	s_and_saveexec_b64 s[78:79], vcc
	s_cbranch_execz .LBB0_1299
	v_add_f32_e32 v92, v92, v93
	s_mov_b32 s67, 0x47800000
	v_fma_f32 v92, v92, s67, 0.5
	v_trunc_f32_e32 v92, v92
	v_mul_f32_e32 v93, 0x2f800000, v92
	v_floor_f32_e32 v93, v93
	v_fmac_f32_e32 v92, 0xcf800000, v93
	v_cvt_u32_f32_e32 v92, v92
	v_cvt_u32_f32_e32 v93, v93
	v_lshlrev_b32_e32 v94, 3, v120
	global_atomic_add_x2 v94, v[92:93], s[6:7]
.LBB0_1299:
	s_or_b64 exec, exec, s[78:79]
	v_or_b32_e32 v92, 48, v242
	v_lshlrev_b32_e32 v93, 13, v92
	v_lshlrev_b32_e32 v94, 16, v192
	v_and_b32_e32 v95, 0xffff0000, v192
	v_lshlrev_b32_e32 v100, 16, v193
	v_and_b32_e32 v101, 0xffff0000, v193
	v_lshlrev_b32_e32 v102, 16, v194
	v_and_b32_e32 v103, 0xffff0000, v194
	v_lshlrev_b32_e32 v104, 16, v195
	v_and_b32_e32 v105, 0xffff0000, v195
	v_pk_fma_f32 v[86:87], v[86:87], v[198:199], v[100:101]
	v_pk_fma_f32 v[84:85], v[84:85], v[196:197], v[94:95]
	v_pk_fma_f32 v[94:95], v[82:83], v[190:191], v[104:105]
	v_pk_fma_f32 v[82:83], v[80:81], v[188:189], v[102:103]
	v_cvt_pk_bf16_f32 v80, v84, v85
	v_cvt_pk_bf16_f32 v81, v86, v87
	v_add_u32_e32 v100, v241, v93
	v_cvt_pk_bf16_f32 v82, v82, v83
	v_cvt_pk_bf16_f32 v83, v94, v95
	global_store_dwordx4 v100, v[80:83], s[20:21]
	v_lshlrev_b32_e32 v84, 16, v80
	v_and_b32_e32 v85, 0xffff0000, v80
	v_lshlrev_b32_e32 v80, 16, v81
	v_and_b32_e32 v81, 0xffff0000, v81
	v_mul_f32_e32 v94, v85, v85
	v_mul_f32_e32 v95, v81, v81
	v_lshlrev_b32_e32 v86, 16, v82
	v_and_b32_e32 v87, 0xffff0000, v82
	v_lshlrev_b32_e32 v82, 16, v83
	v_and_b32_e32 v83, 0xffff0000, v83
	v_fmac_f32_e32 v94, v84, v84
	v_fmac_f32_e32 v95, v80, v80
	v_add_f32_e32 v94, v94, v95
	v_mul_f32_e32 v95, v87, v87
	v_mul_f32_e32 v101, v83, v83
	v_fmac_f32_e32 v95, v86, v86
	v_fmac_f32_e32 v101, v82, v82
	v_add_f32_e32 v95, v95, v101
	v_add_f32_e32 v101, v94, v95
	v_pk_mul_f32 v[94:95], v[186:187], v[80:81]
	v_pk_mul_f32 v[80:81], v[184:185], v[84:85]
	v_pk_mul_f32 v[84:85], v[182:183], v[82:83]
	v_pk_mul_f32 v[82:83], v[180:181], v[86:87]
	v_cvt_pk_bf16_f32 v80, v80, v81
	v_cvt_pk_bf16_f32 v81, v94, v95
	v_lshlrev_b32_e32 v94, 12, v92
	v_cvt_pk_bf16_f32 v82, v82, v83
	v_cvt_pk_bf16_f32 v83, v84, v85
	v_sub_u32_e32 v84, v100, v94
	s_cmp_eq_u32 s32, 3
	s_cbranch_scc1 .Lxg3_6
	global_store_dwordx4 v84, v[80:83], s[22:23]
.Lxg3_6:
	v_lshlrev_b32_e32 v84, 16, v166
	v_and_b32_e32 v85, 0xffff0000, v166
	v_lshlrev_b32_e32 v80, 16, v164
	v_and_b32_e32 v81, 0xffff0000, v164
	v_lshlrev_b32_e32 v82, 16, v165
	v_and_b32_e32 v83, 0xffff0000, v165
	v_lshlrev_b32_e32 v86, 16, v167
	v_and_b32_e32 v87, 0xffff0000, v167
	v_pk_fma_f32 v[78:79], v[78:79], v[170:171], v[82:83]
	v_pk_fma_f32 v[76:77], v[76:77], v[168:169], v[80:81]
	v_pk_fma_f32 v[80:81], v[70:71], v[162:163], v[86:87]
	v_pk_fma_f32 v[70:71], v[68:69], v[160:161], v[84:85]
	v_cvt_pk_bf16_f32 v68, v76, v77
	v_cvt_pk_bf16_f32 v69, v78, v79
	v_add_u32_e32 v82, v144, v93
	v_cvt_pk_bf16_f32 v70, v70, v71
	v_cvt_pk_bf16_f32 v71, v80, v81
	global_store_dwordx4 v82, v[68:71], s[20:21]
	v_lshlrev_b32_e32 v76, 16, v68
	v_and_b32_e32 v77, 0xffff0000, v68
	v_lshlrev_b32_e32 v68, 16, v69
	v_and_b32_e32 v69, 0xffff0000, v69
	v_mul_f32_e32 v80, v77, v77
	v_mul_f32_e32 v81, v69, v69
	v_lshlrev_b32_e32 v78, 16, v70
	v_and_b32_e32 v79, 0xffff0000, v70
	v_lshlrev_b32_e32 v70, 16, v71
	v_and_b32_e32 v71, 0xffff0000, v71
	v_fmac_f32_e32 v80, v76, v76
	v_fmac_f32_e32 v81, v68, v68
	v_add_f32_e32 v80, v80, v81
	v_mul_f32_e32 v81, v79, v79
	v_mul_f32_e32 v83, v71, v71
	v_fmac_f32_e32 v81, v78, v78
	v_fmac_f32_e32 v83, v70, v70
	v_add_f32_e32 v81, v81, v83
	v_add_f32_e32 v80, v80, v81
	v_add_f32_e32 v83, v101, v80
	v_pk_mul_f32 v[80:81], v[158:159], v[68:69]
	v_pk_mul_f32 v[68:69], v[156:157], v[76:77]
	v_pk_mul_f32 v[76:77], v[154:155], v[70:71]
	v_pk_mul_f32 v[70:71], v[152:153], v[78:79]
	ds_swizzle_b32 v78, v83 offset:swizzle(SWAP,16)
	v_cvt_pk_bf16_f32 v68, v68, v69
	v_cvt_pk_bf16_f32 v69, v80, v81
	v_cvt_pk_bf16_f32 v70, v70, v71
	v_cvt_pk_bf16_f32 v71, v76, v77
	v_sub_u32_e32 v76, v82, v94
	s_cmp_eq_u32 s32, 3
	s_cbranch_scc1 .Lxg3_7
	global_store_dwordx4 v76, v[68:71], s[22:23]
.Lxg3_7:
	s_waitcnt lgkmcnt(0)
	s_nop 0
	v_add_f32_e32 v68, v83, v78
	v_mov_b32_e32 v69, v68
	s_nop 1
	v_permlane32_swap_b32_e32 v68, v69
	s_and_saveexec_b64 s[78:79], vcc
	s_cbranch_execz .LBB0_1301
	v_add_f32_e32 v68, v68, v69
	s_mov_b32 s67, 0x47800000
	v_fma_f32 v68, v68, s67, 0.5
	v_trunc_f32_e32 v68, v68
	v_mul_f32_e32 v69, 0x2f800000, v68
	v_floor_f32_e32 v69, v69
	v_fmac_f32_e32 v68, 0xcf800000, v69
	v_cvt_u32_f32_e32 v68, v68
	v_cvt_u32_f32_e32 v69, v69
	v_lshlrev_b32_e32 v70, 3, v92
	global_atomic_add_x2 v70, v[68:69], s[6:7]
.LBB0_1301:
	s_or_b64 exec, exec, s[78:79]
	v_add_u32_e32 v120, 0x80, v242
	v_lshlrev_b32_e32 v121, 13, v120
	v_lshlrev_b32_e32 v122, 16, v140
	v_and_b32_e32 v123, 0xffff0000, v140
	v_lshlrev_b32_e32 v124, 16, v141
	v_and_b32_e32 v125, 0xffff0000, v141
	v_lshlrev_b32_e32 v126, 16, v142
	v_and_b32_e32 v127, 0xffff0000, v142
	v_lshlrev_b32_e32 v132, 16, v143
	v_and_b32_e32 v133, 0xffff0000, v143
	ds_read_b128 v[112:115], v243 offset:2048
	ds_read_b128 v[104:107], v243 offset:2064
	ds_read_b128 v[100:103], v243 offset:6144
	ds_read_b128 v[92:95], v243 offset:6160
	ds_read_b128 v[84:87], v243 offset:2560
	ds_read_b128 v[80:83], v243 offset:2576
	ds_read_b128 v[76:79], v243 offset:6656
	ds_read_b128 v[68:71], v243 offset:6672
	s_waitcnt lgkmcnt(7)
	v_pk_fma_f32 v[62:63], v[62:63], v[114:115], v[124:125]
	v_pk_fma_f32 v[60:61], v[60:61], v[112:113], v[122:123]
	s_waitcnt lgkmcnt(6)
	v_pk_fma_f32 v[122:123], v[58:59], v[106:107], v[132:133]
	v_pk_fma_f32 v[58:59], v[56:57], v[104:105], v[126:127]
	v_cvt_pk_bf16_f32 v56, v60, v61
	v_cvt_pk_bf16_f32 v57, v62, v63
	v_add_u32_e32 v124, v241, v121
	v_cvt_pk_bf16_f32 v58, v58, v59
	v_cvt_pk_bf16_f32 v59, v122, v123
	global_store_dwordx4 v124, v[56:59], s[20:21]
	v_lshlrev_b32_e32 v60, 16, v56
	v_and_b32_e32 v61, 0xffff0000, v56
	v_lshlrev_b32_e32 v56, 16, v57
	v_and_b32_e32 v57, 0xffff0000, v57
	v_mul_f32_e32 v122, v61, v61
	v_mul_f32_e32 v123, v57, v57
	v_lshlrev_b32_e32 v62, 16, v58
	v_and_b32_e32 v63, 0xffff0000, v58
	v_lshlrev_b32_e32 v58, 16, v59
	v_and_b32_e32 v59, 0xffff0000, v59
	v_fmac_f32_e32 v122, v60, v60
	v_fmac_f32_e32 v123, v56, v56
	v_add_f32_e32 v122, v122, v123
	v_mul_f32_e32 v123, v63, v63
	v_mul_f32_e32 v125, v59, v59
	v_fmac_f32_e32 v123, v62, v62
	v_fmac_f32_e32 v125, v58, v58
	v_add_f32_e32 v123, v123, v125
	v_add_f32_e32 v125, v122, v123
	s_waitcnt lgkmcnt(5)
	v_pk_mul_f32 v[122:123], v[102:103], v[56:57]
	v_pk_mul_f32 v[56:57], v[100:101], v[60:61]
	s_waitcnt lgkmcnt(4)
	v_pk_mul_f32 v[60:61], v[94:95], v[58:59]
	v_pk_mul_f32 v[58:59], v[92:93], v[62:63]
	v_cvt_pk_bf16_f32 v56, v56, v57
	v_cvt_pk_bf16_f32 v57, v122, v123
	v_lshlrev_b32_e32 v122, 12, v120
	v_cvt_pk_bf16_f32 v58, v58, v59
	v_cvt_pk_bf16_f32 v59, v60, v61
	v_sub_u32_e32 v60, v124, v122
	s_cmp_eq_u32 s32, 3
	s_cbranch_scc1 .Lxg3_8
	global_store_dwordx4 v60, v[56:59], s[22:23]
.Lxg3_8:
	v_lshlrev_b32_e32 v60, 16, v130
	v_and_b32_e32 v61, 0xffff0000, v130
	v_lshlrev_b32_e32 v56, 16, v128
	v_and_b32_e32 v57, 0xffff0000, v128
	v_lshlrev_b32_e32 v58, 16, v129
	v_and_b32_e32 v59, 0xffff0000, v129
	v_lshlrev_b32_e32 v62, 16, v131
	v_and_b32_e32 v63, 0xffff0000, v131
	s_waitcnt lgkmcnt(3)
	v_pk_fma_f32 v[54:55], v[54:55], v[86:87], v[58:59]
	v_pk_fma_f32 v[52:53], v[52:53], v[84:85], v[56:57]
	s_waitcnt lgkmcnt(2)
	v_pk_fma_f32 v[56:57], v[50:51], v[82:83], v[62:63]
	v_pk_fma_f32 v[50:51], v[48:49], v[80:81], v[60:61]
	v_cvt_pk_bf16_f32 v48, v52, v53
	v_cvt_pk_bf16_f32 v49, v54, v55
	v_add_u32_e32 v58, v144, v121
	v_cvt_pk_bf16_f32 v50, v50, v51
	v_cvt_pk_bf16_f32 v51, v56, v57
	global_store_dwordx4 v58, v[48:51], s[20:21]
	v_lshlrev_b32_e32 v52, 16, v48
	v_and_b32_e32 v53, 0xffff0000, v48
	v_lshlrev_b32_e32 v48, 16, v49
	v_and_b32_e32 v49, 0xffff0000, v49
	v_mul_f32_e32 v56, v53, v53
	v_mul_f32_e32 v57, v49, v49
	v_lshlrev_b32_e32 v54, 16, v50
	v_and_b32_e32 v55, 0xffff0000, v50
	v_lshlrev_b32_e32 v50, 16, v51
	v_and_b32_e32 v51, 0xffff0000, v51
	v_fmac_f32_e32 v56, v52, v52
	v_fmac_f32_e32 v57, v48, v48
	v_add_f32_e32 v56, v56, v57
	v_mul_f32_e32 v57, v55, v55
	v_mul_f32_e32 v59, v51, v51
	v_fmac_f32_e32 v57, v54, v54
	v_fmac_f32_e32 v59, v50, v50
	v_add_f32_e32 v57, v57, v59
	v_add_f32_e32 v56, v56, v57
	v_add_f32_e32 v59, v125, v56
	s_waitcnt lgkmcnt(1)
	v_pk_mul_f32 v[56:57], v[78:79], v[48:49]
	v_pk_mul_f32 v[48:49], v[76:77], v[52:53]
	s_waitcnt lgkmcnt(0)
	v_pk_mul_f32 v[52:53], v[70:71], v[50:51]
	v_pk_mul_f32 v[50:51], v[68:69], v[54:55]
	ds_swizzle_b32 v54, v59 offset:swizzle(SWAP,16)
	v_cvt_pk_bf16_f32 v48, v48, v49
	v_cvt_pk_bf16_f32 v49, v56, v57
	v_cvt_pk_bf16_f32 v50, v50, v51
	v_cvt_pk_bf16_f32 v51, v52, v53
	v_sub_u32_e32 v52, v58, v122
	s_cmp_eq_u32 s32, 3
	s_cbranch_scc1 .Lxg3_9
	global_store_dwordx4 v52, v[48:51], s[22:23]
.Lxg3_9:
	s_waitcnt lgkmcnt(0)
	s_nop 0
	v_add_f32_e32 v48, v59, v54
	v_mov_b32_e32 v49, v48
	s_nop 1
	v_permlane32_swap_b32_e32 v48, v49
	s_and_saveexec_b64 s[78:79], vcc
	s_cbranch_execz .LBB0_1303
	v_add_f32_e32 v48, v48, v49
	s_mov_b32 s67, 0x47800000
	v_fma_f32 v48, v48, s67, 0.5
	v_trunc_f32_e32 v48, v48
	v_mul_f32_e32 v49, 0x2f800000, v48
	v_floor_f32_e32 v49, v49
	v_fmac_f32_e32 v48, 0xcf800000, v49
	v_cvt_u32_f32_e32 v48, v48
	v_cvt_u32_f32_e32 v49, v49
	v_lshlrev_b32_e32 v50, 3, v120
	global_atomic_add_x2 v50, v[48:49], s[6:7]
.LBB0_1303:
	s_or_b64 exec, exec, s[78:79]
	v_add_u32_e32 v48, 0x90, v242
	v_lshlrev_b32_e32 v49, 13, v48
	v_lshlrev_b32_e32 v50, 16, v116
	v_and_b32_e32 v51, 0xffff0000, v116
	v_lshlrev_b32_e32 v52, 16, v117
	v_and_b32_e32 v53, 0xffff0000, v117
	v_lshlrev_b32_e32 v54, 16, v118
	v_and_b32_e32 v55, 0xffff0000, v118
	v_lshlrev_b32_e32 v56, 16, v119
	v_and_b32_e32 v57, 0xffff0000, v119
	v_pk_fma_f32 v[46:47], v[46:47], v[114:115], v[52:53]
	v_pk_fma_f32 v[44:45], v[44:45], v[112:113], v[50:51]
	v_pk_fma_f32 v[50:51], v[42:43], v[106:107], v[56:57]
	v_pk_fma_f32 v[42:43], v[40:41], v[104:105], v[54:55]
	v_cvt_pk_bf16_f32 v40, v44, v45
	v_cvt_pk_bf16_f32 v41, v46, v47
	v_add_u32_e32 v52, v241, v49
	v_cvt_pk_bf16_f32 v42, v42, v43
	v_cvt_pk_bf16_f32 v43, v50, v51
	global_store_dwordx4 v52, v[40:43], s[20:21]
	v_lshlrev_b32_e32 v44, 16, v40
	v_and_b32_e32 v45, 0xffff0000, v40
	v_lshlrev_b32_e32 v40, 16, v41
	v_and_b32_e32 v41, 0xffff0000, v41
	v_mul_f32_e32 v50, v45, v45
	v_mul_f32_e32 v51, v41, v41
	v_lshlrev_b32_e32 v46, 16, v42
	v_and_b32_e32 v47, 0xffff0000, v42
	v_lshlrev_b32_e32 v42, 16, v43
	v_and_b32_e32 v43, 0xffff0000, v43
	v_fmac_f32_e32 v50, v44, v44
	v_fmac_f32_e32 v51, v40, v40
	v_add_f32_e32 v50, v50, v51
	v_mul_f32_e32 v51, v47, v47
	v_mul_f32_e32 v53, v43, v43
	v_fmac_f32_e32 v51, v46, v46
	v_fmac_f32_e32 v53, v42, v42
	v_add_f32_e32 v51, v51, v53
	v_add_f32_e32 v53, v50, v51
	v_pk_mul_f32 v[50:51], v[102:103], v[40:41]
	v_pk_mul_f32 v[40:41], v[100:101], v[44:45]
	v_pk_mul_f32 v[44:45], v[94:95], v[42:43]
	v_pk_mul_f32 v[42:43], v[92:93], v[46:47]
	v_cvt_pk_bf16_f32 v40, v40, v41
	v_cvt_pk_bf16_f32 v41, v50, v51
	v_lshlrev_b32_e32 v50, 12, v48
	v_cvt_pk_bf16_f32 v42, v42, v43
	v_cvt_pk_bf16_f32 v43, v44, v45
	v_sub_u32_e32 v44, v52, v50
	s_cmp_eq_u32 s32, 3
	s_cbranch_scc1 .Lxg3_10
	global_store_dwordx4 v44, v[40:43], s[22:23]
.Lxg3_10:
	v_lshlrev_b32_e32 v44, 16, v110
	v_and_b32_e32 v45, 0xffff0000, v110
	v_lshlrev_b32_e32 v40, 16, v108
	v_and_b32_e32 v41, 0xffff0000, v108
	v_lshlrev_b32_e32 v42, 16, v109
	v_and_b32_e32 v43, 0xffff0000, v109
	v_lshlrev_b32_e32 v46, 16, v111
	v_and_b32_e32 v47, 0xffff0000, v111
	v_pk_fma_f32 v[38:39], v[38:39], v[86:87], v[42:43]
	v_pk_fma_f32 v[36:37], v[36:37], v[84:85], v[40:41]
	v_pk_fma_f32 v[40:41], v[34:35], v[82:83], v[46:47]
	v_pk_fma_f32 v[34:35], v[32:33], v[80:81], v[44:45]
	v_cvt_pk_bf16_f32 v32, v36, v37
	v_cvt_pk_bf16_f32 v33, v38, v39
	v_add_u32_e32 v42, v144, v49
	v_cvt_pk_bf16_f32 v34, v34, v35
	v_cvt_pk_bf16_f32 v35, v40, v41
	global_store_dwordx4 v42, v[32:35], s[20:21]
	v_lshlrev_b32_e32 v36, 16, v32
	v_and_b32_e32 v37, 0xffff0000, v32
	v_lshlrev_b32_e32 v32, 16, v33
	v_and_b32_e32 v33, 0xffff0000, v33
	v_mul_f32_e32 v40, v37, v37
	v_mul_f32_e32 v41, v33, v33
	v_lshlrev_b32_e32 v38, 16, v34
	v_and_b32_e32 v39, 0xffff0000, v34
	v_lshlrev_b32_e32 v34, 16, v35
	v_and_b32_e32 v35, 0xffff0000, v35
	v_fmac_f32_e32 v40, v36, v36
	v_fmac_f32_e32 v41, v32, v32
	v_add_f32_e32 v40, v40, v41
	v_mul_f32_e32 v41, v39, v39
	v_mul_f32_e32 v43, v35, v35
	v_fmac_f32_e32 v41, v38, v38
	v_fmac_f32_e32 v43, v34, v34
	v_add_f32_e32 v41, v41, v43
	v_add_f32_e32 v40, v40, v41
	v_add_f32_e32 v43, v53, v40
	v_pk_mul_f32 v[40:41], v[78:79], v[32:33]
	v_pk_mul_f32 v[32:33], v[76:77], v[36:37]
	v_pk_mul_f32 v[36:37], v[70:71], v[34:35]
	v_pk_mul_f32 v[34:35], v[68:69], v[38:39]
	ds_swizzle_b32 v38, v43 offset:swizzle(SWAP,16)
	v_cvt_pk_bf16_f32 v32, v32, v33
	v_cvt_pk_bf16_f32 v33, v40, v41
	v_cvt_pk_bf16_f32 v34, v34, v35
	v_cvt_pk_bf16_f32 v35, v36, v37
	v_sub_u32_e32 v36, v42, v50
	s_cmp_eq_u32 s32, 3
	s_cbranch_scc1 .Lxg3_11
	global_store_dwordx4 v36, v[32:35], s[22:23]
.Lxg3_11:
	s_waitcnt lgkmcnt(0)
	s_nop 0
	v_add_f32_e32 v32, v43, v38
	v_mov_b32_e32 v33, v32
	s_nop 1
	v_permlane32_swap_b32_e32 v32, v33
	s_and_saveexec_b64 s[78:79], vcc
	s_cbranch_execz .LBB0_1305
	v_add_f32_e32 v32, v32, v33
	s_mov_b32 s67, 0x47800000
	v_fma_f32 v32, v32, s67, 0.5
	v_trunc_f32_e32 v32, v32
	v_mul_f32_e32 v33, 0x2f800000, v32
	v_floor_f32_e32 v33, v33
	v_fmac_f32_e32 v32, 0xcf800000, v33
	v_cvt_u32_f32_e32 v32, v32
	v_cvt_u32_f32_e32 v33, v33
	v_lshlrev_b32_e32 v34, 3, v48
	global_atomic_add_x2 v34, v[32:33], s[6:7]
.LBB0_1305:
	s_or_b64 exec, exec, s[78:79]
	v_add_u32_e32 v32, 0xa0, v242
	v_lshlrev_b32_e32 v33, 13, v32
	v_lshlrev_b32_e32 v34, 16, v96
	v_and_b32_e32 v35, 0xffff0000, v96
	v_lshlrev_b32_e32 v36, 16, v97
	v_and_b32_e32 v37, 0xffff0000, v97
	v_lshlrev_b32_e32 v38, 16, v98
	v_and_b32_e32 v39, 0xffff0000, v98
	v_lshlrev_b32_e32 v40, 16, v99
	v_and_b32_e32 v41, 0xffff0000, v99
	v_pk_fma_f32 v[30:31], v[30:31], v[114:115], v[36:37]
	v_pk_fma_f32 v[28:29], v[28:29], v[112:113], v[34:35]
	v_pk_fma_f32 v[34:35], v[26:27], v[106:107], v[40:41]
	v_pk_fma_f32 v[26:27], v[24:25], v[104:105], v[38:39]
	v_cvt_pk_bf16_f32 v24, v28, v29
	v_cvt_pk_bf16_f32 v25, v30, v31
	v_add_u32_e32 v36, v241, v33
	v_cvt_pk_bf16_f32 v26, v26, v27
	v_cvt_pk_bf16_f32 v27, v34, v35
	global_store_dwordx4 v36, v[24:27], s[20:21]
	v_lshlrev_b32_e32 v28, 16, v24
	v_and_b32_e32 v29, 0xffff0000, v24
	v_lshlrev_b32_e32 v24, 16, v25
	v_and_b32_e32 v25, 0xffff0000, v25
	v_mul_f32_e32 v34, v29, v29
	v_mul_f32_e32 v35, v25, v25
	v_lshlrev_b32_e32 v30, 16, v26
	v_and_b32_e32 v31, 0xffff0000, v26
	v_lshlrev_b32_e32 v26, 16, v27
	v_and_b32_e32 v27, 0xffff0000, v27
	v_fmac_f32_e32 v34, v28, v28
	v_fmac_f32_e32 v35, v24, v24
	v_add_f32_e32 v34, v34, v35
	v_mul_f32_e32 v35, v31, v31
	v_mul_f32_e32 v37, v27, v27
	v_fmac_f32_e32 v35, v30, v30
	v_fmac_f32_e32 v37, v26, v26
	v_add_f32_e32 v35, v35, v37
	v_add_f32_e32 v37, v34, v35
	v_pk_mul_f32 v[34:35], v[102:103], v[24:25]
	v_pk_mul_f32 v[24:25], v[100:101], v[28:29]
	v_pk_mul_f32 v[28:29], v[94:95], v[26:27]
	v_pk_mul_f32 v[26:27], v[92:93], v[30:31]
	v_cvt_pk_bf16_f32 v24, v24, v25
	v_cvt_pk_bf16_f32 v25, v34, v35
	v_lshlrev_b32_e32 v34, 12, v32
	v_cvt_pk_bf16_f32 v26, v26, v27
	v_cvt_pk_bf16_f32 v27, v28, v29
	v_sub_u32_e32 v28, v36, v34
	s_cmp_eq_u32 s32, 3
	s_cbranch_scc1 .Lxg3_12
	global_store_dwordx4 v28, v[24:27], s[22:23]
.Lxg3_12:
	v_lshlrev_b32_e32 v28, 16, v90
	v_and_b32_e32 v29, 0xffff0000, v90
	v_lshlrev_b32_e32 v24, 16, v88
	v_and_b32_e32 v25, 0xffff0000, v88
	v_lshlrev_b32_e32 v26, 16, v89
	v_and_b32_e32 v27, 0xffff0000, v89
	v_lshlrev_b32_e32 v30, 16, v91
	v_and_b32_e32 v31, 0xffff0000, v91
	v_pk_fma_f32 v[22:23], v[22:23], v[86:87], v[26:27]
	v_pk_fma_f32 v[20:21], v[20:21], v[84:85], v[24:25]
	v_pk_fma_f32 v[24:25], v[18:19], v[82:83], v[30:31]
	v_pk_fma_f32 v[18:19], v[16:17], v[80:81], v[28:29]
	v_cvt_pk_bf16_f32 v16, v20, v21
	v_cvt_pk_bf16_f32 v17, v22, v23
	v_add_u32_e32 v26, v144, v33
	v_cvt_pk_bf16_f32 v18, v18, v19
	v_cvt_pk_bf16_f32 v19, v24, v25
	global_store_dwordx4 v26, v[16:19], s[20:21]
	v_lshlrev_b32_e32 v20, 16, v16
	v_and_b32_e32 v21, 0xffff0000, v16
	v_lshlrev_b32_e32 v16, 16, v17
	v_and_b32_e32 v17, 0xffff0000, v17
	v_mul_f32_e32 v24, v21, v21
	v_mul_f32_e32 v25, v17, v17
	v_lshlrev_b32_e32 v22, 16, v18
	v_and_b32_e32 v23, 0xffff0000, v18
	v_lshlrev_b32_e32 v18, 16, v19
	v_and_b32_e32 v19, 0xffff0000, v19
	v_fmac_f32_e32 v24, v20, v20
	v_fmac_f32_e32 v25, v16, v16
	v_add_f32_e32 v24, v24, v25
	v_mul_f32_e32 v25, v23, v23
	v_mul_f32_e32 v27, v19, v19
	v_fmac_f32_e32 v25, v22, v22
	v_fmac_f32_e32 v27, v18, v18
	v_add_f32_e32 v25, v25, v27
	v_add_f32_e32 v24, v24, v25
	v_add_f32_e32 v27, v37, v24
	v_pk_mul_f32 v[24:25], v[78:79], v[16:17]
	v_pk_mul_f32 v[16:17], v[76:77], v[20:21]
	v_pk_mul_f32 v[20:21], v[70:71], v[18:19]
	v_pk_mul_f32 v[18:19], v[68:69], v[22:23]
	ds_swizzle_b32 v22, v27 offset:swizzle(SWAP,16)
	v_cvt_pk_bf16_f32 v16, v16, v17
	v_cvt_pk_bf16_f32 v17, v24, v25
	v_cvt_pk_bf16_f32 v18, v18, v19
	v_cvt_pk_bf16_f32 v19, v20, v21
	v_sub_u32_e32 v20, v26, v34
	s_cmp_eq_u32 s32, 3
	s_cbranch_scc1 .Lxg3_13
	global_store_dwordx4 v20, v[16:19], s[22:23]
.Lxg3_13:
	s_waitcnt lgkmcnt(0)
	s_nop 0
	v_add_f32_e32 v16, v27, v22
	v_mov_b32_e32 v17, v16
	s_nop 1
	v_permlane32_swap_b32_e32 v16, v17
	s_and_saveexec_b64 s[78:79], vcc
	s_cbranch_execz .LBB0_1307
	v_add_f32_e32 v16, v16, v17
	s_mov_b32 s67, 0x47800000
	v_fma_f32 v16, v16, s67, 0.5
	v_trunc_f32_e32 v16, v16
	v_mul_f32_e32 v17, 0x2f800000, v16
	v_floor_f32_e32 v17, v17
	v_fmac_f32_e32 v16, 0xcf800000, v17
	v_cvt_u32_f32_e32 v16, v16
	v_cvt_u32_f32_e32 v17, v17
	v_lshlrev_b32_e32 v18, 3, v32
	global_atomic_add_x2 v18, v[16:17], s[6:7]
.LBB0_1307:
	s_or_b64 exec, exec, s[78:79]
	v_add_u32_e32 v16, 0xb0, v242
	v_lshlrev_b32_e32 v17, 13, v16
	v_lshlrev_b32_e32 v18, 16, v72
	v_and_b32_e32 v19, 0xffff0000, v72
	v_lshlrev_b32_e32 v20, 16, v73
	v_and_b32_e32 v21, 0xffff0000, v73
	v_lshlrev_b32_e32 v22, 16, v74
	v_and_b32_e32 v23, 0xffff0000, v74
	v_lshlrev_b32_e32 v24, 16, v75
	v_and_b32_e32 v25, 0xffff0000, v75
	v_pk_fma_f32 v[14:15], v[14:15], v[114:115], v[20:21]
	v_pk_fma_f32 v[12:13], v[12:13], v[112:113], v[18:19]
	v_pk_fma_f32 v[18:19], v[10:11], v[106:107], v[24:25]
	v_pk_fma_f32 v[10:11], v[8:9], v[104:105], v[22:23]
	v_cvt_pk_bf16_f32 v8, v12, v13
	v_cvt_pk_bf16_f32 v9, v14, v15
	v_add_u32_e32 v20, v241, v17
	v_cvt_pk_bf16_f32 v10, v10, v11
	v_cvt_pk_bf16_f32 v11, v18, v19
	global_store_dwordx4 v20, v[8:11], s[20:21]
	v_lshlrev_b32_e32 v12, 16, v8
	v_and_b32_e32 v13, 0xffff0000, v8
	v_lshlrev_b32_e32 v8, 16, v9
	v_and_b32_e32 v9, 0xffff0000, v9
	v_mul_f32_e32 v18, v13, v13
	v_mul_f32_e32 v19, v9, v9
	v_lshlrev_b32_e32 v14, 16, v10
	v_and_b32_e32 v15, 0xffff0000, v10
	v_lshlrev_b32_e32 v10, 16, v11
	v_and_b32_e32 v11, 0xffff0000, v11
	v_fmac_f32_e32 v18, v12, v12
	v_fmac_f32_e32 v19, v8, v8
	v_add_f32_e32 v18, v18, v19
	v_mul_f32_e32 v19, v15, v15
	v_mul_f32_e32 v21, v11, v11
	v_fmac_f32_e32 v19, v14, v14
	v_fmac_f32_e32 v21, v10, v10
	v_add_f32_e32 v19, v19, v21
	v_add_f32_e32 v21, v18, v19
	v_pk_mul_f32 v[18:19], v[102:103], v[8:9]
	v_pk_mul_f32 v[8:9], v[100:101], v[12:13]
	v_pk_mul_f32 v[12:13], v[94:95], v[10:11]
	v_pk_mul_f32 v[10:11], v[92:93], v[14:15]
	v_cvt_pk_bf16_f32 v8, v8, v9
	v_cvt_pk_bf16_f32 v9, v18, v19
	v_lshlrev_b32_e32 v18, 12, v16
	v_cvt_pk_bf16_f32 v10, v10, v11
	v_cvt_pk_bf16_f32 v11, v12, v13
	v_sub_u32_e32 v12, v20, v18
	s_cmp_eq_u32 s32, 3
	s_cbranch_scc1 .Lxg3_14
	global_store_dwordx4 v12, v[8:11], s[22:23]
.Lxg3_14:
	v_lshlrev_b32_e32 v12, 16, v66
	v_and_b32_e32 v13, 0xffff0000, v66
	v_lshlrev_b32_e32 v8, 16, v64
	v_and_b32_e32 v9, 0xffff0000, v64
	v_lshlrev_b32_e32 v10, 16, v65
	v_and_b32_e32 v11, 0xffff0000, v65
	v_lshlrev_b32_e32 v14, 16, v67
	v_and_b32_e32 v15, 0xffff0000, v67
	v_pk_fma_f32 v[6:7], v[6:7], v[86:87], v[10:11]
	v_pk_fma_f32 v[4:5], v[4:5], v[84:85], v[8:9]
	v_pk_fma_f32 v[8:9], v[2:3], v[82:83], v[14:15]
	v_pk_fma_f32 v[2:3], v[0:1], v[80:81], v[12:13]
	v_cvt_pk_bf16_f32 v0, v4, v5
	v_cvt_pk_bf16_f32 v1, v6, v7
	v_add_u32_e32 v10, v144, v17
	v_cvt_pk_bf16_f32 v2, v2, v3
	v_cvt_pk_bf16_f32 v3, v8, v9
	global_store_dwordx4 v10, v[0:3], s[20:21]
	v_lshlrev_b32_e32 v4, 16, v0
	v_and_b32_e32 v5, 0xffff0000, v0
	v_lshlrev_b32_e32 v0, 16, v1
	v_and_b32_e32 v1, 0xffff0000, v1
	v_mul_f32_e32 v8, v5, v5
	v_mul_f32_e32 v9, v1, v1
	v_lshlrev_b32_e32 v6, 16, v2
	v_and_b32_e32 v7, 0xffff0000, v2
	v_lshlrev_b32_e32 v2, 16, v3
	v_and_b32_e32 v3, 0xffff0000, v3
	v_fmac_f32_e32 v8, v4, v4
	v_fmac_f32_e32 v9, v0, v0
	v_add_f32_e32 v8, v8, v9
	v_mul_f32_e32 v9, v7, v7
	v_mul_f32_e32 v11, v3, v3
	v_fmac_f32_e32 v9, v6, v6
	v_fmac_f32_e32 v11, v2, v2
	v_add_f32_e32 v9, v9, v11
	v_add_f32_e32 v8, v8, v9
	v_add_f32_e32 v11, v21, v8
	v_pk_mul_f32 v[8:9], v[78:79], v[0:1]
	v_pk_mul_f32 v[0:1], v[76:77], v[4:5]
	v_pk_mul_f32 v[4:5], v[70:71], v[2:3]
	v_pk_mul_f32 v[2:3], v[68:69], v[6:7]
	ds_swizzle_b32 v6, v11 offset:swizzle(SWAP,16)
	v_cvt_pk_bf16_f32 v0, v0, v1
	v_cvt_pk_bf16_f32 v1, v8, v9
	v_cvt_pk_bf16_f32 v2, v2, v3
	v_cvt_pk_bf16_f32 v3, v4, v5
	v_sub_u32_e32 v4, v10, v18
	s_cmp_eq_u32 s32, 3
	s_cbranch_scc1 .Lxg3_15
	global_store_dwordx4 v4, v[0:3], s[22:23]
.Lxg3_15:
	s_waitcnt lgkmcnt(0)
	s_nop 0
	v_add_f32_e32 v0, v11, v6
	v_mov_b32_e32 v1, v0
	s_nop 1
	v_permlane32_swap_b32_e32 v0, v1
	s_and_saveexec_b64 s[78:79], vcc
	s_cbranch_execz .LBB0_1309
	v_add_f32_e32 v0, v0, v1
	s_mov_b32 s67, 0x47800000
	v_fma_f32 v0, v0, s67, 0.5
	v_trunc_f32_e32 v0, v0
	v_mul_f32_e32 v1, 0x2f800000, v0
	v_floor_f32_e32 v1, v1
	v_fmac_f32_e32 v0, 0xcf800000, v1
	v_cvt_u32_f32_e32 v0, v0
	v_cvt_u32_f32_e32 v1, v1
	v_lshlrev_b32_e32 v2, 3, v16
	global_atomic_add_x2 v2, v[0:1], s[6:7]
